# st3 + cross-attention first staging skips its drain wait (inputs are register copies), query gains waited after the staging
# baseline (speedup 1.0000x reference)
.LBB0_210:
	s_barrier
	ds_read_b128 v[44:47], v122 offset:16
	ds_read_b128 v[60:63], v122
	ds_read_b128 v[52:55], v122 offset:48
	ds_read_b128 v[56:59], v122 offset:32
	ds_read_b128 v[48:51], v122 offset:80
	ds_read_b128 v[72:75], v122 offset:64
	ds_read_b128 v[64:67], v122 offset:112
	ds_read_b128 v[68:71], v122 offset:96
	s_cmp_eq_u32 s4, 0
	s_cbranch_scc1 .Lxs_nowait
	s_waitcnt vmcnt(0)
.Lxs_nowait:
	v_and_b32_e32 v83, 0xffff0000, v8
	v_lshlrev_b32_e32 v84, 16, v8
	v_mul_f32_e32 v96, v83, v83
	v_lshlrev_b32_e32 v82, 16, v9
	v_fmac_f32_e32 v96, v84, v84
	v_and_b32_e32 v81, 0xffff0000, v9
	v_fmac_f32_e32 v96, v82, v82
	v_lshlrev_b32_e32 v80, 16, v10
	v_fmac_f32_e32 v96, v81, v81
	v_and_b32_e32 v98, 0xffff0000, v10
	v_fmac_f32_e32 v96, v80, v80
	v_lshlrev_b32_e32 v99, 16, v11
	v_fmac_f32_e32 v96, v98, v98
	v_and_b32_e32 v100, 0xffff0000, v11
	v_fmac_f32_e32 v96, v99, v99
	v_lshlrev_b32_e32 v101, 16, v16
	v_fmac_f32_e32 v96, v100, v100
	v_and_b32_e32 v102, 0xffff0000, v16
	v_fmac_f32_e32 v96, v101, v101
	v_lshlrev_b32_e32 v103, 16, v17
	v_fmac_f32_e32 v96, v102, v102
	v_and_b32_e32 v104, 0xffff0000, v17
	v_fmac_f32_e32 v96, v103, v103
	v_lshlrev_b32_e32 v105, 16, v18
	v_fmac_f32_e32 v96, v104, v104
	v_and_b32_e32 v106, 0xffff0000, v18
	v_fmac_f32_e32 v96, v105, v105
	v_lshlrev_b32_e32 v107, 16, v19
	v_fmac_f32_e32 v96, v106, v106
	v_and_b32_e32 v108, 0xffff0000, v19
	v_fmac_f32_e32 v96, v107, v107
	v_lshlrev_b32_e32 v109, 16, v12
	v_fmac_f32_e32 v96, v108, v108
	v_and_b32_e32 v94, 0xffff0000, v12
	v_fmac_f32_e32 v96, v109, v109
	v_lshlrev_b32_e32 v92, 16, v13
	v_fmac_f32_e32 v96, v94, v94
	v_and_b32_e32 v95, 0xffff0000, v13
	v_fmac_f32_e32 v96, v92, v92
	v_lshlrev_b32_e32 v93, 16, v14
	v_fmac_f32_e32 v96, v95, v95
	v_and_b32_e32 v91, 0xffff0000, v14
	v_fmac_f32_e32 v96, v93, v93
	v_lshlrev_b32_e32 v90, 16, v15
	v_fmac_f32_e32 v96, v91, v91
	v_and_b32_e32 v89, 0xffff0000, v15
	v_fmac_f32_e32 v96, v90, v90
	v_lshlrev_b32_e32 v88, 16, v4
	v_fmac_f32_e32 v96, v89, v89
	v_and_b32_e32 v87, 0xffff0000, v4
	v_fmac_f32_e32 v96, v88, v88
	v_lshlrev_b32_e32 v86, 16, v5
	v_fmac_f32_e32 v96, v87, v87
	v_and_b32_e32 v85, 0xffff0000, v5
	v_fmac_f32_e32 v96, v86, v86
	v_and_b32_e32 v76, 0xffff0000, v6
	v_lshlrev_b32_e32 v77, 16, v6
	v_fmac_f32_e32 v96, v85, v85
	v_pk_mul_f32 v[78:79], v[76:77], v[76:77]
	s_cmpk_lg_i32 s4, 0x180
	v_add_f32_e32 v79, v79, v96
	v_add_f32_e32 v110, v78, v79
	v_and_b32_e32 v78, 0xffff0000, v7
	v_lshlrev_b32_e32 v79, 16, v7
	v_pk_mul_f32 v[96:97], v[78:79], v[78:79]
	s_cselect_b64 s[2:3], -1, 0
	v_add_f32_e32 v97, v97, v110
	v_add_f32_e32 v96, v96, v97
	s_nop 1
	s_cmpk_eq_i32 s4, 0x180
	s_waitcnt lgkmcnt(0)
	v_add_f32_dpp v96, v96, v96 quad_perm:[1,0,3,2] row_mask:0xf bank_mask:0xf
	v_fmamk_f32 v96, v96, 0x3c800000, v180
	v_rsq_f32_e32 v96, v96
	s_nop 0
	v_mul_f32_e32 v80, v96, v80
	v_mul_f32_e32 v81, v96, v81
	v_mul_f32_e32 v80, v44, v80
	v_mul_f32_e32 v44, v96, v98
	v_mul_f32_e32 v82, v96, v82
	v_mul_f32_e32 v63, v63, v81
	v_mul_f32_e32 v81, v45, v44
	v_mul_f32_e32 v44, v96, v99
	v_mul_f32_e32 v62, v62, v82
	v_mul_f32_e32 v82, v46, v44
	v_mul_f32_e32 v44, v96, v100
	v_mul_f32_e32 v47, v47, v44
	v_mul_f32_e32 v44, v96, v101
	v_mul_f32_e32 v56, v56, v44
	v_mul_f32_e32 v44, v96, v102
	v_mul_f32_e32 v57, v57, v44
	v_mul_f32_e32 v44, v96, v103
	v_mul_f32_e32 v58, v58, v44
	v_mul_f32_e32 v44, v96, v104
	v_mul_f32_e32 v59, v59, v44
	v_mul_f32_e32 v44, v96, v105
	v_mul_f32_e32 v52, v52, v44
	v_mul_f32_e32 v44, v96, v106
	v_mul_f32_e32 v53, v53, v44
	v_mul_f32_e32 v44, v96, v107
	v_mul_f32_e32 v54, v54, v44
	v_mul_f32_e32 v44, v96, v108
	v_mul_f32_e32 v55, v55, v44
	v_mul_f32_e32 v44, v96, v109
	v_mul_f32_e32 v72, v72, v44
	v_mul_f32_e32 v44, v96, v94
	v_mul_f32_e32 v73, v73, v44
	v_mul_f32_e32 v44, v96, v92
	v_mul_f32_e32 v74, v74, v44
	v_mul_f32_e32 v44, v96, v95
	v_mul_f32_e32 v75, v75, v44
	v_mul_f32_e32 v44, v96, v93
	v_mul_f32_e32 v48, v48, v44
	v_mul_f32_e32 v44, v96, v91
	v_mul_f32_e32 v49, v49, v44
	v_mul_f32_e32 v44, v96, v90
	v_mul_f32_e32 v50, v50, v44
	v_mul_f32_e32 v44, v96, v89
	v_mul_f32_e32 v51, v51, v44
	v_mul_f32_e32 v44, v96, v88
	s_cmp_eq_u32 s4, 0
	s_cbranch_scc0 .Lxg_skip
	v_bfe_u32 v129, v0, 4, 2
	v_mul_u32_u24_e32 v171, 0x1200, v116
	v_lshl_add_u32 v129, v129, 3, v171
	v_add_u32_e32 v129, 0x1000, v129
	global_load_dwordx2 v[150:151], v129, s[88:89]
	global_load_dwordx2 v[152:153], v129, s[88:89] offset:32
	global_load_dwordx2 v[154:155], v129, s[88:89] offset:64
	global_load_dwordx2 v[156:157], v129, s[88:89] offset:96
	global_load_dwordx2 v[158:159], v129, s[88:89] offset:128
	global_load_dwordx2 v[160:161], v129, s[88:89] offset:160
	global_load_dwordx2 v[162:163], v129, s[88:89] offset:192
	global_load_dwordx2 v[164:165], v129, s[88:89] offset:224
	global_load_dwordx2 v[166:167], v129, s[88:89] offset:256
	global_load_dwordx2 v[168:169], v129, s[88:89] offset:288
	global_load_dwordx2 v[248:249], v129, s[88:89] offset:320
	global_load_dwordx2 v[250:251], v129, s[88:89] offset:352
	global_load_dwordx2 v[252:253], v129, s[88:89] offset:384
	global_load_dwordx2 v[254:255], v129, s[88:89] offset:416
.Lxg_skip:
	s_waitcnt vmcnt(14)
	s_cmpk_eq_i32 s4, 0x180
	v_mul_f32_e32 v68, v68, v44
	v_mul_f32_e32 v44, v96, v87
	v_mul_f32_e32 v69, v69, v44
	v_mul_f32_e32 v44, v96, v86
	v_mul_f32_e32 v70, v44, v70
	v_mul_f32_e32 v44, v96, v85
	v_mul_f32_e32 v71, v44, v71
	v_mul_f32_e32 v44, v96, v77
	v_mul_f32_e32 v64, v44, v64
	v_mul_f32_e32 v44, v96, v76
	v_mul_f32_e32 v65, v44, v65
	v_mul_f32_e32 v44, v96, v79
	v_mul_f32_e32 v84, v96, v84
	v_mul_f32_e32 v83, v96, v83
	v_mul_f32_e32 v66, v44, v66
	v_mul_f32_e32 v44, v96, v78
	v_mul_f32_e32 v60, v60, v84
	v_mul_f32_e32 v61, v61, v83
	v_mul_f32_e32 v67, v44, v67
	v_cvt_pk_bf16_f32 v44, v60, v61
	v_cvt_pk_bf16_f32 v45, v62, v63
	v_cvt_pk_bf16_f32 v46, v80, v81
	v_cvt_pk_bf16_f32 v47, v82, v47
	ds_write_b128 v132, v[44:47]
	v_cvt_pk_bf16_f32 v44, v56, v57
	v_cvt_pk_bf16_f32 v45, v58, v59
	v_cvt_pk_bf16_f32 v46, v52, v53
	v_cvt_pk_bf16_f32 v47, v54, v55
	ds_write_b128 v132, v[44:47] offset:16
	v_cvt_pk_bf16_f32 v44, v72, v73
	v_cvt_pk_bf16_f32 v45, v74, v75
	v_cvt_pk_bf16_f32 v46, v48, v49
	v_cvt_pk_bf16_f32 v47, v50, v51
	ds_write_b128 v132, v[44:47] offset:32
	v_cvt_pk_bf16_f32 v44, v68, v69
	v_cvt_pk_bf16_f32 v45, v70, v71
	v_cvt_pk_bf16_f32 v46, v64, v65
	v_cvt_pk_bf16_f32 v47, v66, v67
	ds_write_b128 v132, v[44:47] offset:48
	ds_write_b16 v135, v28 offset:36864
	ds_write_b16_d16_hi v135, v28 offset:37392
	ds_write_b16 v135, v29 offset:37920
	ds_write_b16_d16_hi v135, v29 offset:38448
	ds_write_b16 v135, v30 offset:38976
	ds_write_b16_d16_hi v135, v30 offset:39504
	ds_write_b16 v135, v31 offset:40032
	ds_write_b16_d16_hi v135, v31 offset:40560
	ds_write_b16 v135, v32 offset:41088
	ds_write_b16_d16_hi v135, v32 offset:41616
	ds_write_b16 v135, v33 offset:42144
	ds_write_b16_d16_hi v135, v33 offset:42672
	ds_write_b16 v135, v34 offset:43200
	ds_write_b16_d16_hi v135, v34 offset:43728
	ds_write_b16 v135, v35 offset:44256
	ds_write_b16_d16_hi v135, v35 offset:44784
	ds_write_b16 v135, v36 offset:45312
	ds_write_b16_d16_hi v135, v36 offset:45840
	ds_write_b16 v135, v37 offset:46368
	ds_write_b16_d16_hi v135, v37 offset:46896
	ds_write_b16 v135, v38 offset:47424
	ds_write_b16_d16_hi v135, v38 offset:47952
	ds_write_b16 v135, v39 offset:48480
	ds_write_b16_d16_hi v135, v39 offset:49008
	ds_write_b16 v135, v40 offset:49536
	ds_write_b16_d16_hi v135, v40 offset:50064
	ds_write_b16 v135, v41 offset:50592
	ds_write_b16_d16_hi v135, v41 offset:51120
	ds_write_b16 v135, v42 offset:51648
	ds_write_b16_d16_hi v135, v42 offset:52176
	ds_write_b16 v135, v43 offset:52704
	ds_write_b16_d16_hi v135, v43 offset:53232
	s_waitcnt lgkmcnt(0)
	s_barrier
	s_cbranch_scc1 .LBB0_212
	v_lshl_add_u64 v[4:5], v[126:127], 0, s[4:5]
	s_mov_b64 s[6:7], 0xdbe0080
	v_add_co_u32_e32 v40, vcc, 0xdbe0000, v4
	v_lshl_add_u64 v[16:17], v[4:5], 0, s[6:7]
	s_nop 0
	v_addc_co_u32_e32 v41, vcc, 0, v5, vcc
	global_load_dwordx4 v[8:11], v[40:41], off offset:128
	global_load_dwordx4 v[4:7], v[16:17], off offset:48
	global_load_dwordx4 v[12:15], v[16:17], off offset:32
	s_nop 0
	global_load_dwordx4 v[16:19], v[16:17], off offset:16
	s_nop 0
	global_load_dwordx4 v[28:31], v[40:41], off offset:640
	global_load_dwordx4 v[32:35], v[40:41], off offset:656
	global_load_dwordx4 v[36:39], v[40:41], off offset:672
	s_nop 0
	global_load_dwordx4 v[40:43], v[40:41], off offset:688
	s_mov_b64 s[6:7], s[0:1]
	s_branch .LBB0_213
